# combo1 + hand-written lean grid-barrier fast path at the 4 in-loop barriers (static generation, non-returning top add, leaders poll top counter, no TOPGEN hop)
# speedup vs baseline: 1.0210x; 1.0109x over previous
; __device__ __forceinline__ unsigned xb_ld(unsigned* p)              { return __hip_atomic_load(p, __ATOMIC_RELAXED, __HIP_MEMORY_SCOPE_AGENT); }
; __device__ __forceinline__ unsigned xb_add(unsigned* p, unsigned v) { return __hip_atomic_fetch_add(p, v, __ATOMIC_RELAXED, __HIP_MEMORY_SCOPE_AGENT); }
; #define XB_SPIN(cond, bar) do { unsigned _sp = 0; while (cond) { __builtin_amdgcn_s_sleep(1); \
;     if ((++_sp & 255u) == 0u) { if (xb_ld(&(bar)[XB_TMO])) break; if (_sp > XB_SPIN_CAP) { atomicAdd(&(bar)[XB_TMO], 1u); break; } } } } while (0)
; __device__ __forceinline__ void xcd_barrier(const XcdBarrier& b) {
;     asm volatile("s_waitcnt vmcnt(0)" ::: "memory");
;     __syncthreads();
;     if (threadIdx.x == 0) {
;         unsigned* bar = b.bar;
;         __builtin_amdgcn_s_waitcnt(0);
;         unsigned nloc = b.st[0], nx = b.st[1];
;         if (nloc == 0u) { xcd_barrier_complete(bar, b.x, nloc, nx); b.st[0] = nloc; b.st[1] = nx; }
;         const unsigned old = xb_add(&bar[XB_XSUB(b.x)], 1u);
;         const unsigned gen = old / nloc;
;         if (old + 1u == (gen + 1u) * nloc) {
;             __builtin_amdgcn_fence(__ATOMIC_RELEASE, "agent");
;             asm volatile("s_waitcnt vmcnt(0)" ::: "memory");
;             const unsigned og = xb_add(&bar[XB_TOP], 1u);
;             const unsigned tg = og / nx;
;             if (og + 1u == (tg + 1u) * nx) xb_add(&bar[XB_TOPGEN], 1u);
;             else XB_SPIN(xb_ld(&bar[XB_TOPGEN]) == tg, bar);
;             __builtin_amdgcn_fence(__ATOMIC_ACQUIRE, "agent");
;             xb_add(&bar[XB_XGEN(b.x)], 1u);
;             asm volatile("s_waitcnt vmcnt(0)" ::: "memory");
;         } else {
;             XB_SPIN(xb_ld(&bar[XB_XGEN(b.x)]) == gen, bar);
;             __builtin_amdgcn_fence(__ATOMIC_ACQUIRE, "agent");
;             asm volatile("s_waitcnt vmcnt(0)" ::: "memory");
;         }
;     }
;     __syncthreads();
.LBB0_207:
	s_getreg_b32 s2, hwreg(HW_REG_XCC_ID, 0, 4)
	s_waitcnt vmcnt(0)
	s_barrier
	s_mov_b64 s[0:1], exec
	v_readlane_b32 s4, v253, 2
	v_readlane_b32 s5, v253, 3
	s_and_b64 s[4:5], s[0:1], s[4:5]
	s_mov_b64 exec, s[4:5]
	s_cbranch_execz .LBB0_259
	v_mov_b32_e32 v0, 0x20020
	s_waitcnt vmcnt(0) lgkmcnt(0)
	ds_read2_b32 v[2:3], v0 offset1:1
	s_and_b32 s3, s2, 15
	s_lshl_b32 s3, s3, 8
	s_add_u32 s6, s78, 0x1701400
	s_addc_u32 s7, s79, 0
	s_add_u32 s6, s6, s3
	s_addc_u32 s7, s7, 0
	s_add_u32 s8, s6, 0x1000
	s_addc_u32 s9, s7, 0
	s_add_u32 s10, s78, 0x1703400
	s_addc_u32 s11, s79, 0
	s_lshl_b32 s29, s66, 2
	s_add_i32 s29, s29, 1
	s_waitcnt lgkmcnt(0)
	v_readfirstlane_b32 s30, v2
	v_readfirstlane_b32 s31, v3
	s_nop 3
	s_cmp_eq_u32 s30, 0
	s_cbranch_scc1 .Lxb_slow_n
	global_atomic_add v2, v173, v212, s[6:7] sc0
	s_add_i32 s32, s29, 1
	s_mul_i32 s5, s32, s30
	s_mul_i32 s32, s32, s31
	s_waitcnt vmcnt(0)
	v_readfirstlane_b32 s3, v2
	s_nop 3
	s_add_i32 s3, s3, 1
	s_cmp_lg_u32 s3, s5
	s_cbranch_scc1 .Lxb_local_n
	buffer_wbl2 sc1
	s_waitcnt vmcnt(0)
	global_atomic_add v173, v212, s[10:11]
	s_mov_b32 s3, 0
.Lxb_top_n:
	global_load_dword v2, v173, s[10:11] sc1
	s_waitcnt vmcnt(0)
	v_readfirstlane_b32 s5, v2
	s_nop 3
	s_cmp_ge_u32 s5, s32
	s_cbranch_scc1 .Lxb_top_n_done
	s_sleep 1
	s_add_i32 s3, s3, 1
	s_cmp_lt_u32 s3, 0x40000
	s_cbranch_scc1 .Lxb_top_n
.Lxb_top_n_done:
	buffer_inv sc1
	global_atomic_add v173, v212, s[8:9]
	s_waitcnt vmcnt(0)
	s_branch .LBB0_259
.Lxb_local_n:
	s_mov_b32 s3, 0
.Lxb_gen_n:
	global_load_dword v2, v173, s[8:9] sc1
	s_waitcnt vmcnt(0)
	v_readfirstlane_b32 s5, v2
	s_nop 3
	s_cmp_lg_u32 s5, s29
	s_cbranch_scc1 .Lxb_gen_n_done
	s_sleep 1
	s_add_i32 s3, s3, 1
	s_cmp_lt_u32 s3, 0x40000
	s_cbranch_scc1 .Lxb_gen_n
.Lxb_gen_n_done:
	buffer_inv sc1
	s_waitcnt vmcnt(0)
	s_branch .LBB0_259
.Lxb_slow_n:
	v_readlane_b32 s3, v254, 44
	s_waitcnt vmcnt(0) expcnt(0) lgkmcnt(0)
	s_and_b32 s2, s2, 15
	v_mov_b32_e32 v0, s3
	ds_read_b32 v2, v0
	v_readlane_b32 s3, v254, 45
	s_waitcnt lgkmcnt(0)
	v_cmp_ne_u32_e32 vcc, 0, v2
	v_mov_b32_e32 v0, s3
	ds_read_b32 v0, v0
	s_cbranch_vccnz .LBB0_223
	s_mov_b32 s3, 1
	s_branch .LBB0_211

; __device__ __forceinline__ unsigned xb_ld(unsigned* p)              { return __hip_atomic_load(p, __ATOMIC_RELAXED, __HIP_MEMORY_SCOPE_AGENT); }
; __device__ __forceinline__ unsigned xb_add(unsigned* p, unsigned v) { return __hip_atomic_fetch_add(p, v, __ATOMIC_RELAXED, __HIP_MEMORY_SCOPE_AGENT); }
; #define XB_SPIN(cond, bar) do { unsigned _sp = 0; while (cond) { __builtin_amdgcn_s_sleep(1); \
;     if ((++_sp & 255u) == 0u) { if (xb_ld(&(bar)[XB_TMO])) break; if (_sp > XB_SPIN_CAP) { atomicAdd(&(bar)[XB_TMO], 1u); break; } } } } while (0)
; __device__ __forceinline__ void xcd_barrier(const XcdBarrier& b) {
;     asm volatile("s_waitcnt vmcnt(0)" ::: "memory");
;     __syncthreads();
;     if (threadIdx.x == 0) {
;         unsigned* bar = b.bar;
;         __builtin_amdgcn_s_waitcnt(0);
;         unsigned nloc = b.st[0], nx = b.st[1];
;         if (nloc == 0u) { xcd_barrier_complete(bar, b.x, nloc, nx); b.st[0] = nloc; b.st[1] = nx; }
;         const unsigned old = xb_add(&bar[XB_XSUB(b.x)], 1u);
;         const unsigned gen = old / nloc;
;         if (old + 1u == (gen + 1u) * nloc) {
;             __builtin_amdgcn_fence(__ATOMIC_RELEASE, "agent");
;             asm volatile("s_waitcnt vmcnt(0)" ::: "memory");
;             const unsigned og = xb_add(&bar[XB_TOP], 1u);
;             const unsigned tg = og / nx;
;             if (og + 1u == (tg + 1u) * nx) xb_add(&bar[XB_TOPGEN], 1u);
;             else XB_SPIN(xb_ld(&bar[XB_TOPGEN]) == tg, bar);
;             __builtin_amdgcn_fence(__ATOMIC_ACQUIRE, "agent");
;             xb_add(&bar[XB_XGEN(b.x)], 1u);
;             asm volatile("s_waitcnt vmcnt(0)" ::: "memory");
;         } else {
;             XB_SPIN(xb_ld(&bar[XB_XGEN(b.x)]) == gen, bar);
;             __builtin_amdgcn_fence(__ATOMIC_ACQUIRE, "agent");
;             asm volatile("s_waitcnt vmcnt(0)" ::: "memory");
;         }
;     }
;     __syncthreads();
.LBB0_386:
	s_getreg_b32 s2, hwreg(HW_REG_XCC_ID, 0, 4)
	s_waitcnt vmcnt(0)
	v_writelane_b32 v255, s0, 13
	s_waitcnt vmcnt(0)
	s_barrier
	v_writelane_b32 v255, s1, 14
	s_mov_b64 s[0:1], exec
	v_readlane_b32 s4, v253, 2
	v_readlane_b32 s5, v253, 3
	s_and_b64 s[4:5], s[0:1], s[4:5]
	s_mov_b64 exec, s[4:5]
	s_cbranch_execz .LBB0_439
	v_mov_b32_e32 v0, 0x20020
	s_waitcnt vmcnt(0) lgkmcnt(0)
	ds_read2_b32 v[2:3], v0 offset1:1
	s_and_b32 s3, s2, 15
	s_lshl_b32 s3, s3, 8
	s_add_u32 s6, s78, 0x1701400
	s_addc_u32 s7, s79, 0
	s_add_u32 s6, s6, s3
	s_addc_u32 s7, s7, 0
	s_add_u32 s8, s6, 0x1000
	s_addc_u32 s9, s7, 0
	s_add_u32 s10, s78, 0x1703400
	s_addc_u32 s11, s79, 0
	s_lshl_b32 s29, s66, 2
	s_add_i32 s29, s29, 2
	s_waitcnt lgkmcnt(0)
	v_readfirstlane_b32 s30, v2
	v_readfirstlane_b32 s31, v3
	s_nop 3
	s_cmp_eq_u32 s30, 0
	s_cbranch_scc1 .Lxb_slow_i
	global_atomic_add v2, v173, v212, s[6:7] sc0
	s_add_i32 s32, s29, 1
	s_mul_i32 s5, s32, s30
	s_mul_i32 s32, s32, s31
	s_waitcnt vmcnt(0)
	v_readfirstlane_b32 s3, v2
	s_nop 3
	s_add_i32 s3, s3, 1
	s_cmp_lg_u32 s3, s5
	s_cbranch_scc1 .Lxb_local_i
	buffer_wbl2 sc1
	s_waitcnt vmcnt(0)
	global_atomic_add v173, v212, s[10:11]
	s_mov_b32 s3, 0

; __device__ __forceinline__ unsigned xb_ld(unsigned* p)              { return __hip_atomic_load(p, __ATOMIC_RELAXED, __HIP_MEMORY_SCOPE_AGENT); }
; __device__ __forceinline__ unsigned xb_add(unsigned* p, unsigned v) { return __hip_atomic_fetch_add(p, v, __ATOMIC_RELAXED, __HIP_MEMORY_SCOPE_AGENT); }
; #define XB_SPIN(cond, bar) do { unsigned _sp = 0; while (cond) { __builtin_amdgcn_s_sleep(1); \
;     if ((++_sp & 255u) == 0u) { if (xb_ld(&(bar)[XB_TMO])) break; if (_sp > XB_SPIN_CAP) { atomicAdd(&(bar)[XB_TMO], 1u); break; } } } } while (0)
; __device__ __forceinline__ void xcd_barrier(const XcdBarrier& b) {
;     asm volatile("s_waitcnt vmcnt(0)" ::: "memory");
;     __syncthreads();
;     if (threadIdx.x == 0) {
;         unsigned* bar = b.bar;
;         __builtin_amdgcn_s_waitcnt(0);
;         unsigned nloc = b.st[0], nx = b.st[1];
;         if (nloc == 0u) { xcd_barrier_complete(bar, b.x, nloc, nx); b.st[0] = nloc; b.st[1] = nx; }
;         const unsigned old = xb_add(&bar[XB_XSUB(b.x)], 1u);
;         const unsigned gen = old / nloc;
;         if (old + 1u == (gen + 1u) * nloc) {
;             __builtin_amdgcn_fence(__ATOMIC_RELEASE, "agent");
;             asm volatile("s_waitcnt vmcnt(0)" ::: "memory");
;             const unsigned og = xb_add(&bar[XB_TOP], 1u);
;             const unsigned tg = og / nx;
;             if (og + 1u == (tg + 1u) * nx) xb_add(&bar[XB_TOPGEN], 1u);
;             else XB_SPIN(xb_ld(&bar[XB_TOPGEN]) == tg, bar);
;             __builtin_amdgcn_fence(__ATOMIC_ACQUIRE, "agent");
;             xb_add(&bar[XB_XGEN(b.x)], 1u);
;             asm volatile("s_waitcnt vmcnt(0)" ::: "memory");
;         } else {
;             XB_SPIN(xb_ld(&bar[XB_XGEN(b.x)]) == gen, bar);
;             __builtin_amdgcn_fence(__ATOMIC_ACQUIRE, "agent");
;             asm volatile("s_waitcnt vmcnt(0)" ::: "memory");
;         }
;     }
;     __syncthreads();
.LBB0_534:
	s_and_b64 vcc, exec, s[0:1]
	s_mov_b32 s93, s4
	s_cbranch_vccz .LBB0_441
	s_getreg_b32 s2, hwreg(HW_REG_XCC_ID, 0, 4)
	s_waitcnt vmcnt(0)
	s_barrier
	s_mov_b64 s[0:1], exec
	v_readlane_b32 s4, v253, 2
	v_readlane_b32 s5, v253, 3
	v_readlane_b32 s72, v254, 48
	v_readlane_b32 s80, v254, 50
	v_readlane_b32 s82, v254, 52
	v_readlane_b32 s92, v254, 54
	v_readlane_b32 s94, v254, 56
	v_readlane_b32 s98, v254, 58
	v_readlane_b32 s54, v254, 60
	v_readlane_b32 s56, v254, 62
	v_readlane_b32 s60, v255, 0
	v_readlane_b32 s62, v255, 2
	v_readlane_b32 s22, v255, 21
	s_and_b64 s[4:5], s[0:1], s[4:5]
	v_readlane_b32 s73, v254, 49
	v_readlane_b32 s81, v254, 51
	v_readlane_b32 s83, v254, 53
	v_readlane_b32 s93, v254, 55
	v_readlane_b32 s95, v254, 57
	v_readlane_b32 s99, v254, 59
	v_readlane_b32 s55, v254, 61
	v_readlane_b32 s57, v254, 63
	v_readlane_b32 s61, v255, 1
	v_readlane_b32 s63, v255, 3
	v_readlane_b32 s33, v255, 4
	v_readlane_b32 s85, v255, 5
	v_readlane_b32 s25, v254, 41
	v_readlane_b32 s28, v254, 43
	v_readlane_b32 s23, v255, 22
	s_mov_b64 exec, s[4:5]
	s_cbranch_execz .LBB0_587
	v_mov_b32_e32 v0, 0x20020
	s_waitcnt vmcnt(0) lgkmcnt(0)
	ds_read2_b32 v[2:3], v0 offset1:1
	s_and_b32 s3, s2, 15
	s_lshl_b32 s3, s3, 8
	s_add_u32 s6, s78, 0x1701400
	s_addc_u32 s7, s79, 0
	s_add_u32 s6, s6, s3
	s_addc_u32 s7, s7, 0
	s_add_u32 s8, s6, 0x1000
	s_addc_u32 s9, s7, 0
	s_add_u32 s10, s78, 0x1703400
	s_addc_u32 s11, s79, 0
	v_readlane_b32 s29, v255, 21
	s_nop 3
	s_lshl_b32 s29, s29, 2
	s_add_i32 s29, s29, 3
	s_waitcnt lgkmcnt(0)
	v_readfirstlane_b32 s30, v2
	v_readfirstlane_b32 s31, v3
	s_nop 3
	s_cmp_eq_u32 s30, 0
	s_cbranch_scc1 .Lxb_slow_m
	global_atomic_add v2, v173, v212, s[6:7] sc0
	s_add_i32 s32, s29, 1
	s_mul_i32 s5, s32, s30
	s_mul_i32 s32, s32, s31
	s_waitcnt vmcnt(0)
	v_readfirstlane_b32 s3, v2
	s_nop 3
	s_add_i32 s3, s3, 1
	s_cmp_lg_u32 s3, s5
	s_cbranch_scc1 .Lxb_local_m
	buffer_wbl2 sc1
	s_waitcnt vmcnt(0)
	global_atomic_add v173, v212, s[10:11]
	s_mov_b32 s3, 0

; __device__ __forceinline__ unsigned xb_ld(unsigned* p)              { return __hip_atomic_load(p, __ATOMIC_RELAXED, __HIP_MEMORY_SCOPE_AGENT); }
; __device__ __forceinline__ unsigned xb_add(unsigned* p, unsigned v) { return __hip_atomic_fetch_add(p, v, __ATOMIC_RELAXED, __HIP_MEMORY_SCOPE_AGENT); }
; #define XB_SPIN(cond, bar) do { unsigned _sp = 0; while (cond) { __builtin_amdgcn_s_sleep(1); \
;     if ((++_sp & 255u) == 0u) { if (xb_ld(&(bar)[XB_TMO])) break; if (_sp > XB_SPIN_CAP) { atomicAdd(&(bar)[XB_TMO], 1u); break; } } } } while (0)
; __device__ __forceinline__ void xcd_barrier(const XcdBarrier& b) {
;     asm volatile("s_waitcnt vmcnt(0)" ::: "memory");
;     __syncthreads();
;     if (threadIdx.x == 0) {
;         unsigned* bar = b.bar;
;         __builtin_amdgcn_s_waitcnt(0);
;         unsigned nloc = b.st[0], nx = b.st[1];
;         if (nloc == 0u) { xcd_barrier_complete(bar, b.x, nloc, nx); b.st[0] = nloc; b.st[1] = nx; }
;         const unsigned old = xb_add(&bar[XB_XSUB(b.x)], 1u);
;         const unsigned gen = old / nloc;
;         if (old + 1u == (gen + 1u) * nloc) {
;             __builtin_amdgcn_fence(__ATOMIC_RELEASE, "agent");
;             asm volatile("s_waitcnt vmcnt(0)" ::: "memory");
;             const unsigned og = xb_add(&bar[XB_TOP], 1u);
;             const unsigned tg = og / nx;
;             if (og + 1u == (tg + 1u) * nx) xb_add(&bar[XB_TOPGEN], 1u);
;             else XB_SPIN(xb_ld(&bar[XB_TOPGEN]) == tg, bar);
;             __builtin_amdgcn_fence(__ATOMIC_ACQUIRE, "agent");
;             xb_add(&bar[XB_XGEN(b.x)], 1u);
;             asm volatile("s_waitcnt vmcnt(0)" ::: "memory");
;         } else {
;             XB_SPIN(xb_ld(&bar[XB_XGEN(b.x)]) == gen, bar);
;             __builtin_amdgcn_fence(__ATOMIC_ACQUIRE, "agent");
;             asm volatile("s_waitcnt vmcnt(0)" ::: "memory");
;         }
;     }
;     __syncthreads();
.LBB0_683:
	v_readlane_b32 s2, v255, 11
	v_readlane_b32 s3, v255, 12
	s_mov_b64 s[0:1], -1
	s_and_b64 vcc, exec, s[2:3]
	v_readlane_b32 s12, v255, 6
	s_mov_b64 s[26:27], 0x1000
	v_readlane_b32 s13, v255, 7
	s_cbranch_vccz .LBB0_190
	s_getreg_b32 s2, hwreg(HW_REG_XCC_ID, 0, 4)
	s_waitcnt vmcnt(0)
	s_barrier
	s_mov_b64 s[0:1], exec
	v_readlane_b32 s4, v253, 2
	v_readlane_b32 s5, v253, 3
	s_and_b64 s[4:5], s[0:1], s[4:5]
	s_mov_b64 exec, s[4:5]
	s_cbranch_execz .LBB0_189
	v_mov_b32_e32 v0, 0x20020
	s_waitcnt vmcnt(0) lgkmcnt(0)
	ds_read2_b32 v[2:3], v0 offset1:1
	s_and_b32 s3, s2, 15
	s_lshl_b32 s3, s3, 8
	s_add_u32 s6, s78, 0x1701400
	s_addc_u32 s7, s79, 0
	s_add_u32 s6, s6, s3
	s_addc_u32 s7, s7, 0
	s_add_u32 s8, s6, 0x1000
	s_addc_u32 s9, s7, 0
	s_add_u32 s10, s78, 0x1703400
	s_addc_u32 s11, s79, 0
	s_mov_b32 s29, 4
	s_waitcnt lgkmcnt(0)
	v_readfirstlane_b32 s30, v2
	v_readfirstlane_b32 s31, v3
	s_nop 3
	s_cmp_eq_u32 s30, 0
	s_cbranch_scc1 .Lxb_slow_o
	global_atomic_add v2, v173, v212, s[6:7] sc0
	s_add_i32 s32, s29, 1
	s_mul_i32 s5, s32, s30
	s_mul_i32 s32, s32, s31
	s_waitcnt vmcnt(0)
	v_readfirstlane_b32 s3, v2
	s_nop 3
	s_add_i32 s3, s3, 1
	s_cmp_lg_u32 s3, s5
	s_cbranch_scc1 .Lxb_local_o
	buffer_wbl2 sc1
	s_waitcnt vmcnt(0)
	global_atomic_add v173, v212, s[10:11]
	s_mov_b32 s3, 0
